# plus: flag_wait issues its cache invalidate before the first flag load (overlaps the round trip)
# baseline (speedup 1.0000x reference)
.LBB0_755:
	s_add_u32 s20, s0, 0x4200
	s_addc_u32 s21, s1, 0
	s_and_b64 vcc, exec, s[94:95]
	s_cbranch_vccnz .LBB0_772
	v_mbcnt_lo_u32_b32 v0, -1, 0
	v_mbcnt_hi_u32_b32 v0, -1, v0
	s_nop 0
	v_cmp_eq_u32_e32 vcc, 0, v0
	s_and_saveexec_b64 s[8:9], vcc
	s_cbranch_execz .LBB0_771
	buffer_inv sc1
	v_mov_b32_e32 v0, 0
	global_load_dword v1, v0, s[42:43] sc1
	s_min_i32 s14, s33, 64
	s_waitcnt vmcnt(0)
	v_cmp_le_u32_e32 vcc, s14, v1
	s_cbranch_vccnz .LBB0_770
	s_mov_b32 s15, 1
	s_branch .LBB0_760

.LBB0_770:
	s_waitcnt vmcnt(0)
	s_waitcnt vmcnt(0)

.LBB0_863:
	s_and_b64 vcc, exec, s[94:95]
	s_cbranch_vccnz .LBB0_880
	v_mbcnt_lo_u32_b32 v0, -1, 0
	v_mbcnt_hi_u32_b32 v0, -1, v0
	s_nop 0
	v_cmp_eq_u32_e32 vcc, 0, v0
	s_and_saveexec_b64 s[8:9], vcc
	s_cbranch_execz .LBB0_879
	buffer_inv sc1
	v_mov_b32_e32 v0, 0
	global_load_dword v1, v0, s[22:23] sc1
	s_min_i32 s14, s33, 16
	s_waitcnt vmcnt(0)
	v_cmp_le_u32_e32 vcc, s14, v1
	s_cbranch_vccnz .LBB0_878
	s_mov_b32 s15, 1
	s_branch .LBB0_868

.LBB0_878:
	s_waitcnt vmcnt(0) lgkmcnt(0)
	s_waitcnt vmcnt(0)

.LBB0_1093:
	s_and_b32 s0, s92, 3
	s_cmp_lg_u32 s0, 0
	s_cbranch_scc1 .LBB0_1114
	s_and_b64 vcc, exec, s[94:95]
	s_cbranch_vccnz .LBB0_1111
	v_mbcnt_lo_u32_b32 v0, -1, 0
	v_mbcnt_hi_u32_b32 v0, -1, v0
	s_nop 0
	v_cmp_eq_u32_e32 vcc, 0, v0
	s_and_saveexec_b64 s[0:1], vcc
	s_cbranch_execz .LBB0_1110
	buffer_inv sc1
	v_mov_b32_e32 v0, 0
	global_load_dword v1, v0, s[12:13] sc1
	s_waitcnt vmcnt(0)
	v_cmp_le_u32_e32 vcc, s14, v1
	s_cbranch_vccnz .LBB0_1109
	s_mov_b32 s15, 1
	s_branch .LBB0_1099
